# v48: v47 + RG-LRU pass 2 tile loop: waits for the conv-output LDS reads moved below the k-slice 2/3 MFMAs (counted lgkmcnt(4) in front of the k-slice 3 MFMAs)
# baseline (speedup 1.0000x reference)
.LBB0_602:
	v_add_u32_e32 v97, 0, v172
	v_add_u32_e32 v92, 0x10c00, v97
	v_add_u32_e32 v98, 0x10c40, v97
	ds_read_b128 v[92:95], v92
	ds_read_b128 v[102:105], v98
	v_add_u32_e32 v228, 0x10c80, v97
	ds_read_b128 v[228:231], v228
	v_add_u32_e32 v232, 0x10cc0, v97
	ds_read_b128 v[232:235], v232
	v_add_u32_e32 v173, 0, v171
	v_add_u32_e32 v180, 0x8c00, v173
	s_waitcnt lgkmcnt(3)
	v_mfma_f32_16x16x32_bf16 v[98:101], v[92:95], v[0:3], 0
	s_add_i32 s14, s14, -1
	v_add_u32_e32 v172, 0x1100, v172
	v_add_u32_e32 v171, 0x2100, v171
	v_mfma_f32_16x16x32_bf16 v[110:113], v[92:95], v[32:35], 0
	v_add_u32_e32 v195, 0x400, v173
	s_cmp_eq_u32 s14, 0
	v_mfma_f32_16x16x32_bf16 v[106:109], v[92:95], v[16:19], 0
	v_mfma_f32_16x16x32_bf16 v[92:95], v[92:95], v[48:51], 0
	s_waitcnt lgkmcnt(2)
	v_mfma_f32_16x16x32_bf16 v[114:117], v[102:105], v[4:7], v[98:101]
	v_mfma_f32_16x16x32_bf16 v[98:101], v[102:105], v[36:39], v[110:113]
	v_mfma_f32_16x16x32_bf16 v[174:177], v[102:105], v[20:23], v[106:109]
	v_mfma_f32_16x16x32_bf16 v[106:109], v[102:105], v[52:55], v[92:95]
	v_add_u32_e32 v97, 0x8800, v173
	s_waitcnt lgkmcnt(1)
	v_mfma_f32_16x16x32_bf16 v[102:105], v[228:231], v[8:11], v[114:117]
	v_mfma_f32_16x16x32_bf16 v[114:117], v[228:231], v[24:27], v[174:177]
	s_nop 2
	ds_read2_b32 v[174:175], v97 offset1:16
	ds_read2_b32 v[176:177], v97 offset0:132 offset1:148
	ds_read2_b32 v[178:179], v180 offset0:8 offset1:24
	ds_read2_b32 v[180:181], v180 offset0:140 offset1:156
	v_mfma_f32_16x16x32_bf16 v[98:101], v[228:231], v[40:43], v[98:101]
	v_mfma_f32_16x16x32_bf16 v[106:109], v[228:231], v[56:59], v[106:109]
	s_waitcnt lgkmcnt(4)
	v_mfma_f32_16x16x32_bf16 v[102:105], v[232:235], v[12:15], v[102:105]
	v_mfma_f32_16x16x32_bf16 v[110:113], v[232:235], v[28:31], v[114:117]
	v_mfma_f32_16x16x32_bf16 v[98:101], v[232:235], v[44:47], v[98:101]
	s_waitcnt lgkmcnt(3)
	v_mov_b32_e32 v183, v174
	s_waitcnt lgkmcnt(0)
	v_mov_b32_e32 v184, v181
	s_nop 2
	v_fmamk_f32 v97, v102, 0xbfb8aa3b, v163
	v_fmamk_f32 v102, v103, 0xbfb8aa3b, v163
	v_fmamk_f32 v103, v104, 0xbfb8aa3b, v163
	v_mfma_f32_16x16x32_bf16 v[92:95], v[232:235], v[60:63], v[106:109]
	v_fmamk_f32 v104, v105, 0xbfb8aa3b, v163
	v_fmamk_f32 v98, v98, 0xbfb8aa3b, v164
	v_fmamk_f32 v99, v99, 0xbfb8aa3b, v164
	v_fmamk_f32 v100, v100, 0xbfb8aa3b, v164
	v_fmamk_f32 v101, v101, 0xbfb8aa3b, v164
	v_fmamk_f32 v105, v110, 0xbfb8aa3b, v168
	s_nop 1
	v_fmamk_f32 v92, v92, 0xbfb8aa3b, v167
	v_fmamk_f32 v106, v111, 0xbfb8aa3b, v168
	s_nop 0
	v_fmamk_f32 v93, v93, 0xbfb8aa3b, v167
	v_fmamk_f32 v107, v112, 0xbfb8aa3b, v168
	v_fmamk_f32 v94, v94, 0xbfb8aa3b, v167
	v_fmamk_f32 v108, v113, 0xbfb8aa3b, v168
	v_exp_f32_e32 v97, v97
	v_exp_f32_e32 v98, v98
	v_exp_f32_e32 v102, v102
	v_exp_f32_e32 v99, v99
	v_exp_f32_e32 v103, v103
	v_exp_f32_e32 v100, v100
	v_exp_f32_e32 v104, v104
	v_exp_f32_e32 v101, v101
	v_exp_f32_e32 v105, v105
	v_exp_f32_e32 v92, v92
	v_exp_f32_e32 v106, v106
	v_fmamk_f32 v95, v95, 0xbfb8aa3b, v167
	v_exp_f32_e32 v93, v93
	v_exp_f32_e32 v107, v107
	v_exp_f32_e32 v94, v94
	v_exp_f32_e32 v108, v108
	v_exp_f32_e32 v95, v95
	v_add_f32_e32 v97, 1.0, v97
	v_add_f32_e32 v98, 1.0, v98
	v_add_f32_e32 v102, 1.0, v102
	v_add_f32_e32 v99, 1.0, v99
	v_add_f32_e32 v103, 1.0, v103
	v_add_f32_e32 v100, 1.0, v100
	v_add_f32_e32 v104, 1.0, v104
	v_add_f32_e32 v101, 1.0, v101
	v_add_f32_e32 v105, 1.0, v105
	v_add_f32_e32 v92, 1.0, v92
	v_add_f32_e32 v106, 1.0, v106
	v_rcp_f32_e32 v97, v97
	v_add_f32_e32 v93, 1.0, v93
	v_add_f32_e32 v107, 1.0, v107
	v_add_f32_e32 v94, 1.0, v94
	v_add_f32_e32 v108, 1.0, v108
	v_rcp_f32_e32 v109, v98
	v_rcp_f32_e32 v98, v102
	v_rcp_f32_e32 v110, v99
	v_rcp_f32_e32 v99, v103
	v_rcp_f32_e32 v111, v100
	v_rcp_f32_e32 v100, v104
	v_rcp_f32_e32 v112, v101
	v_rcp_f32_e32 v101, v105
	v_rcp_f32_e32 v105, v92
	v_rcp_f32_e32 v92, v106
	v_rcp_f32_e32 v113, v93
	v_rcp_f32_e32 v93, v107
	v_rcp_f32_e32 v107, v94
	v_rcp_f32_e32 v94, v108
	v_add_f32_e32 v95, 1.0, v95
	v_rcp_f32_e32 v174, v95
	v_mul_f32_e32 v95, v97, v165
	v_mul_f32_e32 v97, v98, v165
	v_mul_f32_e32 v98, v99, v165
	v_mul_f32_e32 v99, v100, v165
	v_mul_f32_e32 v100, v101, v166
	v_mul_f32_e32 v92, v92, v166
	v_mul_f32_e32 v93, v93, v166
	v_mul_f32_e32 v94, v94, v166
	v_mov_b32_e32 v101, v92
	v_exp_f32_e32 v182, v95
	v_mov_b32_e32 v114, v177
	v_exp_f32_e32 v177, v97
	v_exp_f32_e32 v92, v100
	v_exp_f32_e32 v115, v101
	v_exp_f32_e32 v181, v99
	v_exp_f32_e32 v117, v93
	v_exp_f32_e32 v185, v94
	v_mov_b32_e32 v116, v179
	v_exp_f32_e32 v179, v98
	v_fma_f32 v93, -v182, v182, 1.0
	v_fma_f32 v94, -v177, v177, 1.0
	v_fma_f32 v99, -v92, v92, 1.0
	v_fma_f32 v100, -v115, v115, 1.0
	v_max_f32_e32 v93, 0, v93
	v_fma_f32 v97, -v181, v181, 1.0
	v_fma_f32 v101, -v117, v117, 1.0
	v_fma_f32 v102, -v185, v185, 1.0
	v_max_f32_e32 v94, 0, v94
	v_max_f32_e32 v99, 0, v99
	v_max_f32_e32 v100, 0, v100
	v_sqrt_f32_e32 v93, v93
	v_fma_f32 v95, -v179, v179, 1.0
	v_mul_f32_e32 v98, v182, v177
	v_mul_f32_e32 v103, v92, v115
	v_max_f32_e32 v97, 0, v97
	v_max_f32_e32 v101, 0, v101
	v_max_f32_e32 v102, 0, v102
	v_sqrt_f32_e32 v104, v94
	v_sqrt_f32_e32 v186, v99
	v_sqrt_f32_e32 v187, v100
	v_max_f32_e32 v95, 0, v95
	v_mul_f32_e32 v98, v179, v98
	v_mul_f32_e32 v103, v117, v103
	v_sqrt_f32_e32 v108, v97
	v_sqrt_f32_e32 v188, v101
	v_sqrt_f32_e32 v189, v102
	v_sqrt_f32_e32 v106, v95
	v_mul_f32_e32 v95, v181, v98
	v_mul_f32_e32 v97, v185, v103
	ds_bpermute_b32 v94, v129, v95
	ds_bpermute_b32 v98, v170, v95
	ds_bpermute_b32 v100, v131, v95
	ds_bpermute_b32 v102, v169, v95
	ds_bpermute_b32 v95, v129, v97
	ds_bpermute_b32 v99, v170, v97
	ds_bpermute_b32 v101, v131, v97
	ds_bpermute_b32 v103, v169, v97
	v_mul_f32_e32 v97, v109, v93
	v_mul_f32_e32 v104, v110, v104
	v_mul_f32_e32 v93, v105, v186
	v_mul_f32_e32 v110, v113, v187
	v_pk_mul_f32 v[186:187], v[182:183], v[96:97]
	v_mul_f32_e32 v108, v112, v108
	v_mul_f32_e32 v112, v107, v188
	v_mul_f32_e32 v174, v174, v189
	v_pk_fma_f32 v[188:189], v[182:183], v[96:97], v[186:187] op_sel_hi:[1,1,0]
	v_mov_b32_e32 v97, v175
	v_mov_b32_e32 v105, v189
	v_pk_mul_f32 v[188:189], v[92:93], v[96:97]
	v_pk_mul_f32 v[190:191], v[176:177], v[104:105]
	v_pk_fma_f32 v[192:193], v[92:93], v[96:97], v[188:189] op_sel_hi:[1,1,0]
	v_mul_f32_e32 v106, v111, v106
	v_pk_fma_f32 v[104:105], v[176:177], v[104:105], v[190:191] op_sel_hi:[1,1,0]
	v_mov_b32_e32 v111, v193
	v_mov_b32_e32 v107, v105
	v_pk_mul_f32 v[104:105], v[110:111], v[114:115]
	v_pk_mul_f32 v[192:193], v[178:179], v[106:107]
	v_pk_fma_f32 v[110:111], v[110:111], v[114:115], v[104:105] op_sel_hi:[1,1,0]
	v_pk_fma_f32 v[106:107], v[178:179], v[106:107], v[192:193] op_sel_hi:[1,1,0]
	v_mov_b32_e32 v113, v111
	v_mov_b32_e32 v109, v107
	v_pk_mul_f32 v[106:107], v[112:113], v[116:117]
	v_pk_mul_f32 v[110:111], v[180:181], v[108:109]
	v_pk_fma_f32 v[112:113], v[112:113], v[116:117], v[106:107] op_sel_hi:[1,1,0]
	v_pk_fma_f32 v[108:109], v[180:181], v[108:109], v[110:111] op_sel:[0,0,1] op_sel_hi:[1,1,0]
	v_mov_b32_e32 v175, v113
	v_pk_mul_f32 v[202:203], v[174:175], v[184:185]
	ds_bpermute_b32 v112, v129, v108
	v_pk_fma_f32 v[174:175], v[174:175], v[184:185], v[202:203] op_sel:[0,0,1] op_sel_hi:[1,1,0]
	ds_bpermute_b32 v113, v129, v174
	ds_bpermute_b32 v198, v170, v108
	ds_bpermute_b32 v199, v170, v174
	ds_bpermute_b32 v200, v131, v108
	ds_bpermute_b32 v201, v131, v174
	ds_bpermute_b32 v108, v169, v108
	ds_bpermute_b32 v109, v169, v174
	s_waitcnt lgkmcnt(6)
	v_pk_fma_f32 v[94:95], v[142:143], v[94:95], v[112:113]
	s_nop 0
	v_cndmask_b32_e64 v93, v142, v94, s[58:59]
	s_waitcnt lgkmcnt(4)
	v_pk_fma_f32 v[98:99], v[94:95], v[98:99], v[198:199]
	v_cndmask_b32_e64 v97, v143, v95, s[58:59]
	v_cndmask_b32_e64 v93, v93, v98, s[60:61]
	s_waitcnt lgkmcnt(2)
	v_pk_fma_f32 v[94:95], v[98:99], v[100:101], v[200:201]
	v_cndmask_b32_e64 v97, v97, v99, s[60:61]
	v_cndmask_b32_e64 v93, v93, v94, s[62:63]
	s_waitcnt lgkmcnt(0)
	v_pk_fma_f32 v[142:143], v[94:95], v[102:103], v[108:109]
	v_cndmask_b32_e64 v94, v97, v95, s[62:63]
	v_cndmask_b32_e64 v93, v93, v142, s[56:57]
	v_cndmask_b32_e64 v94, v94, v143, s[56:57]
	v_fmac_f32_e32 v187, v182, v93
	v_fmac_f32_e32 v189, v92, v94
	v_fmac_f32_e32 v190, v177, v187
	v_fmac_f32_e32 v104, v115, v189
	v_fmac_f32_e32 v192, v179, v190
	v_fmac_f32_e32 v106, v117, v104
	v_fmac_f32_e32 v110, v181, v192
	v_fmac_f32_e32 v202, v185, v106
	ds_write2_b32 v173, v187, v189 offset1:16
	ds_write2_b32 v173, v190, v104 offset0:132 offset1:148
	ds_write2_b32 v195, v192, v106 offset0:8 offset1:24
	ds_write2_b32 v195, v110, v202 offset0:140 offset1:156
	s_cbranch_scc0 .LBB0_602
	s_branch .LBB0_581
